# ERES0/ERES1 row stores marked nt (streaming: written once, read next by other XCDs after the barrier)
# speedup vs baseline: 1.0110x; 1.0110x over previous
.LBB0_119:
	s_or_b64 exec, exec, s[44:45]
	v_ashrrev_i32_e32 v19, 31, v18
	v_lshlrev_b64 v[18:19], 11, v[18:19]
	v_lshl_add_u64 v[20:21], v[60:61], 0, v[18:19]
	v_lshl_add_u64 v[18:19], v[62:63], 0, v[18:19]
	global_load_dwordx4 v[30:33], v[20:21], off
	global_load_dwordx4 v[26:29], v[18:19], off
	global_load_dwordx4 v[22:25], v[20:21], off offset:1024
	s_nop 0
	global_load_dwordx4 v[18:21], v[18:19], off offset:1024
	s_waitcnt vmcnt(8)
	ds_bpermute_b32 v51, v72, v50
	s_waitcnt lgkmcnt(0)
	v_add_f32_e32 v50, v50, v51
	ds_bpermute_b32 v51, v73, v50
	s_waitcnt lgkmcnt(0)
	v_add_f32_e32 v50, v50, v51
	ds_bpermute_b32 v51, v74, v50
	s_waitcnt lgkmcnt(0)
	v_add_f32_e32 v50, v50, v51
	ds_bpermute_b32 v51, v75, v50
	s_waitcnt lgkmcnt(0)
	v_add_f32_e32 v50, v50, v51
	ds_bpermute_b32 v51, v76, v50
	s_waitcnt lgkmcnt(0)
	v_add_f32_e32 v50, v50, v51
	ds_bpermute_b32 v51, v77, v50
	s_waitcnt lgkmcnt(0)
	v_add_f32_e32 v50, v50, v51
	v_fmamk_f32 v50, v50, 0x3a800000, v229
	v_cmp_gt_f32_e32 vcc, s5, v50
	v_mul_f32_e32 v51, 0x4f800000, v50
	s_nop 0
	v_cndmask_b32_e32 v50, v50, v51, vcc
	v_sqrt_f32_e32 v51, v50
	s_nop 0
	v_add_u32_e32 v52, -1, v51
	v_fma_f32 v53, -v52, v51, v50
	v_cmp_ge_f32_e64 s[44:45], 0, v53
	v_add_u32_e32 v53, 1, v51
	s_nop 0
	v_cndmask_b32_e64 v52, v51, v52, s[44:45]
	v_fma_f32 v51, -v53, v51, v50
	v_cmp_lt_f32_e64 s[44:45], 0, v51
	s_nop 1
	v_cndmask_b32_e64 v51, v52, v53, s[44:45]
	v_mul_f32_e32 v52, 0x37800000, v51
	v_cndmask_b32_e32 v51, v51, v52, vcc
	v_cmp_class_f32_e32 vcc, v50, v230
	s_mov_b64 s[44:45], -1
	s_nop 0
	v_cndmask_b32_e32 v50, v51, v50, vcc
	v_div_scale_f32 v51, s[18:19], v50, v50, 1.0
	v_rcp_f32_e32 v52, v51
	s_nop 0
	v_fma_f32 v53, -v51, v52, 1.0
	v_fmac_f32_e32 v52, v53, v52
	v_div_scale_f32 v53, vcc, 1.0, v50, 1.0
	v_mul_f32_e32 v70, v53, v52
	v_fma_f32 v71, -v51, v70, v53
	v_fmac_f32_e32 v70, v71, v52
	v_fma_f32 v51, -v51, v70, v53
	v_div_fmas_f32 v51, v51, v52, v70
	v_div_fixup_f32 v70, v51, v50, 1.0
	s_waitcnt vmcnt(5)
	v_lshlrev_b32_e32 v52, 16, v42
	v_and_b32_e32 v53, 0xffff0000, v42
	v_lshlrev_b32_e32 v42, 16, v43
	v_and_b32_e32 v43, 0xffff0000, v43
	v_lshlrev_b32_e32 v50, 16, v46
	v_and_b32_e32 v51, 0xffff0000, v46
	v_pk_mul_f32 v[52:53], v[70:71], v[52:53] op_sel_hi:[0,1]
	v_lshlrev_b32_e32 v46, 16, v47
	v_and_b32_e32 v47, 0xffff0000, v47
	v_pk_mul_f32 v[42:43], v[70:71], v[42:43] op_sel_hi:[0,1]
	v_pk_fma_f32 v[50:51], v[6:7], v[52:53], v[50:51]
	v_pk_fma_f32 v[52:53], v[8:9], v[42:43], v[46:47]
	v_lshlrev_b32_e32 v46, 16, v44
	v_and_b32_e32 v47, 0xffff0000, v44
	v_lshlrev_b32_e32 v42, 16, v48
	v_and_b32_e32 v43, 0xffff0000, v48
	v_pk_mul_f32 v[46:47], v[70:71], v[46:47] op_sel_hi:[0,1]
	v_lshlrev_b32_e32 v44, 16, v45
	v_and_b32_e32 v45, 0xffff0000, v45
	v_pk_fma_f32 v[42:43], v[14:15], v[46:47], v[42:43]
	v_lshlrev_b32_e32 v46, 16, v49
	v_and_b32_e32 v47, 0xffff0000, v49
	v_pk_mul_f32 v[44:45], v[70:71], v[44:45] op_sel_hi:[0,1]
	v_pk_fma_f32 v[44:45], v[16:17], v[44:45], v[46:47]
	s_and_b64 vcc, exec, s[26:27]
	s_cbranch_vccz .LBB0_121
	v_cvt_pk_bf16_f32 v46, v50, v51
	v_cvt_pk_bf16_f32 v47, v52, v53
	v_cvt_pk_bf16_f32 v48, v42, v43
	v_cvt_pk_bf16_f32 v49, v44, v45
	global_store_dwordx4 v[68:69], v[46:49], off nt
	v_lshlrev_b32_e32 v79, 16, v47
	v_lshlrev_b32_e32 v78, 16, v46
	v_and_b32_e32 v47, 0xffff0000, v47
	v_and_b32_e32 v46, 0xffff0000, v46
	v_pk_mul_f32 v[46:47], v[46:47], v[46:47]
	s_mov_b64 s[44:45], 0
	v_pk_fma_f32 v[46:47], v[78:79], v[78:79], v[46:47]
	v_lshlrev_b32_e32 v79, 16, v49
	v_lshlrev_b32_e32 v78, 16, v48
	v_and_b32_e32 v49, 0xffff0000, v49
	v_and_b32_e32 v48, 0xffff0000, v48
	v_pk_mul_f32 v[48:49], v[48:49], v[48:49]
	v_add_f32_e32 v46, v46, v47
	v_pk_fma_f32 v[48:49], v[78:79], v[78:79], v[48:49]
	s_nop 0
	v_add_f32_e32 v46, v46, v48
	v_add_f32_e32 v48, v46, v49
.LBB0_121:
	v_lshlrev_b64 v[46:47], 12, v[66:67]
	s_andn2_b64 vcc, exec, s[44:45]
	v_lshl_add_u64 v[46:47], v[58:59], 0, v[46:47]
	s_cbranch_vccnz .LBB0_123
	v_mov_b32_e32 v48, 0
	global_store_dwordx4 v[46:47], v[50:53], off nt
	global_store_dwordx4 v[46:47], v[42:45], off offset:16 nt

.LBB0_127:
	v_cvt_pk_bf16_f32 v38, v42, v43
	v_cvt_pk_bf16_f32 v39, v44, v45
	v_cvt_pk_bf16_f32 v40, v34, v35
	v_cvt_pk_bf16_f32 v41, v36, v37
	global_store_dwordx4 v[68:69], v[38:41], off offset:1024 nt
	v_lshlrev_b32_e32 v51, 16, v39
	v_lshlrev_b32_e32 v50, 16, v38
	v_and_b32_e32 v39, 0xffff0000, v39
	v_and_b32_e32 v38, 0xffff0000, v38
	v_pk_mul_f32 v[38:39], v[38:39], v[38:39]
	s_nop 0
	v_pk_fma_f32 v[38:39], v[50:51], v[50:51], v[38:39]
	s_nop 0
	v_add_f32_e32 v38, v48, v38
	v_add_f32_e32 v49, v38, v39
	v_lshlrev_b32_e32 v39, 16, v41
	v_lshlrev_b32_e32 v38, 16, v40
	v_and_b32_e32 v41, 0xffff0000, v41
	v_and_b32_e32 v40, 0xffff0000, v40
	v_pk_mul_f32 v[40:41], v[40:41], v[40:41]
	s_nop 0
	v_pk_fma_f32 v[38:39], v[38:39], v[38:39], v[40:41]
	s_nop 0
	v_add_f32_e32 v38, v49, v38
	v_add_f32_e32 v38, v38, v39
	s_cbranch_execnz .LBB0_125
.LBB0_128:
	v_mov_b32_e32 v38, v48
	global_store_dwordx4 v[46:47], v[42:45], off offset:2048 nt
	global_store_dwordx4 v[46:47], v[34:37], off offset:2064 nt
	s_and_b64 vcc, exec, s[44:45]
	s_cbranch_vccnz .LBB0_126

.LBB0_132:
	ds_bpermute_b32 v34, v72, v65
	s_waitcnt lgkmcnt(0)
	v_add_f32_e32 v34, v65, v34
	ds_bpermute_b32 v35, v73, v34
	v_ashrrev_i32_e32 v65, 31, v64
	s_waitcnt lgkmcnt(0)
	v_add_f32_e32 v34, v34, v35
	ds_bpermute_b32 v35, v74, v34
	s_waitcnt lgkmcnt(0)
	v_add_f32_e32 v34, v34, v35
	ds_bpermute_b32 v35, v75, v34
	s_waitcnt lgkmcnt(0)
	v_add_f32_e32 v34, v34, v35
	ds_bpermute_b32 v35, v76, v34
	s_waitcnt lgkmcnt(0)
	v_add_f32_e32 v34, v34, v35
	ds_bpermute_b32 v35, v77, v34
	s_waitcnt lgkmcnt(0)
	v_add_f32_e32 v34, v34, v35
	v_fmamk_f32 v34, v34, 0x3a800000, v229
	v_cmp_gt_f32_e32 vcc, s5, v34
	v_mul_f32_e32 v35, 0x4f800000, v34
	s_nop 0
	v_cndmask_b32_e32 v34, v34, v35, vcc
	v_sqrt_f32_e32 v35, v34
	s_nop 0
	v_add_u32_e32 v36, -1, v35
	v_fma_f32 v37, -v36, v35, v34
	v_cmp_ge_f32_e64 s[46:47], 0, v37
	v_add_u32_e32 v37, 1, v35
	s_nop 0
	v_cndmask_b32_e64 v36, v35, v36, s[46:47]
	v_fma_f32 v35, -v37, v35, v34
	v_cmp_lt_f32_e64 s[46:47], 0, v35
	s_nop 1
	v_cndmask_b32_e64 v35, v36, v37, s[46:47]
	v_mul_f32_e32 v36, 0x37800000, v35
	v_cndmask_b32_e32 v35, v35, v36, vcc
	v_cmp_class_f32_e32 vcc, v34, v230
	s_mov_b64 s[46:47], -1
	s_nop 0
	v_cndmask_b32_e32 v34, v35, v34, vcc
	v_div_scale_f32 v35, s[18:19], v34, v34, 1.0
	v_rcp_f32_e32 v36, v35
	s_nop 0
	v_fma_f32 v37, -v35, v36, 1.0
	v_fmac_f32_e32 v36, v37, v36
	v_div_scale_f32 v37, vcc, 1.0, v34, 1.0
	v_mul_f32_e32 v38, v37, v36
	v_fma_f32 v39, -v35, v38, v37
	v_fmac_f32_e32 v38, v39, v36
	v_fma_f32 v35, -v35, v38, v37
	v_div_fmas_f32 v35, v35, v36, v38
	v_div_fixup_f32 v38, v35, v34, 1.0
	v_lshlrev_b64 v[34:35], 11, v[64:65]
	s_waitcnt vmcnt(2)
	v_lshlrev_b32_e32 v36, 16, v26
	v_and_b32_e32 v37, 0xffff0000, v26
	v_lshlrev_b32_e32 v26, 16, v27
	v_and_b32_e32 v27, 0xffff0000, v27
	v_lshl_add_u64 v[40:41], s[36:37], 0, v[34:35]
	v_lshlrev_b32_e32 v34, 16, v30
	v_and_b32_e32 v35, 0xffff0000, v30
	v_pk_mul_f32 v[36:37], v[38:39], v[36:37] op_sel_hi:[0,1]
	v_lshlrev_b32_e32 v30, 16, v31
	v_and_b32_e32 v31, 0xffff0000, v31
	v_pk_mul_f32 v[26:27], v[38:39], v[26:27] op_sel_hi:[0,1]
	v_pk_fma_f32 v[34:35], v[6:7], v[36:37], v[34:35]
	v_pk_fma_f32 v[36:37], v[8:9], v[26:27], v[30:31]
	v_lshlrev_b32_e32 v30, 16, v28
	v_and_b32_e32 v31, 0xffff0000, v28
	v_lshlrev_b32_e32 v26, 16, v32
	v_and_b32_e32 v27, 0xffff0000, v32
	v_pk_mul_f32 v[30:31], v[38:39], v[30:31] op_sel_hi:[0,1]
	v_lshlrev_b32_e32 v28, 16, v29
	v_and_b32_e32 v29, 0xffff0000, v29
	v_pk_fma_f32 v[26:27], v[14:15], v[30:31], v[26:27]
	v_lshlrev_b32_e32 v30, 16, v33
	v_and_b32_e32 v31, 0xffff0000, v33
	v_pk_mul_f32 v[28:29], v[38:39], v[28:29] op_sel_hi:[0,1]
	v_pk_fma_f32 v[28:29], v[16:17], v[28:29], v[30:31]
	s_and_b64 vcc, exec, s[44:45]
	v_lshlrev_b32_e32 v30, 1, v54
	s_cbranch_vccnz .LBB0_134
	v_mov_b32_e32 v31, v1
	v_cvt_pk_bf16_f32 v42, v34, v35
	v_cvt_pk_bf16_f32 v43, v36, v37
	v_lshl_add_u64 v[32:33], v[40:41], 0, v[30:31]
	v_cvt_pk_bf16_f32 v44, v26, v27
	v_cvt_pk_bf16_f32 v45, v28, v29
	global_store_dwordx4 v[32:33], v[42:45], off nt
	v_lshlrev_b32_e32 v33, 16, v43
	v_lshlrev_b32_e32 v32, 16, v42
	v_and_b32_e32 v43, 0xffff0000, v43
	v_and_b32_e32 v42, 0xffff0000, v42
	v_pk_mul_f32 v[42:43], v[42:43], v[42:43]
	s_mov_b64 s[46:47], 0
	v_pk_fma_f32 v[32:33], v[32:33], v[32:33], v[42:43]
	v_lshlrev_b32_e32 v43, 16, v45
	v_lshlrev_b32_e32 v42, 16, v44
	v_and_b32_e32 v45, 0xffff0000, v45
	v_and_b32_e32 v44, 0xffff0000, v44
	v_pk_mul_f32 v[44:45], v[44:45], v[44:45]
	v_add_f32_e32 v31, v32, v33
	v_pk_fma_f32 v[42:43], v[42:43], v[42:43], v[44:45]
	s_nop 0
	v_add_f32_e32 v31, v31, v42
	v_add_f32_e32 v42, v31, v43
.LBB0_134:
	v_lshlrev_b64 v[32:33], 12, v[64:65]
	s_andn2_b64 vcc, exec, s[46:47]
	v_lshl_add_u64 v[32:33], v[58:59], 0, v[32:33]
	s_cbranch_vccnz .LBB0_136
	v_mov_b32_e32 v42, 0
	global_store_dwordx4 v[32:33], v[34:37], off nt
	global_store_dwordx4 v[32:33], v[26:29], off offset:16 nt

.LBB0_139:
	v_mov_b32_e32 v31, v1
	v_cvt_pk_bf16_f32 v22, v26, v27
	v_cvt_pk_bf16_f32 v23, v28, v29
	v_lshl_add_u64 v[30:31], v[40:41], 0, v[30:31]
	v_cvt_pk_bf16_f32 v24, v18, v19
	v_cvt_pk_bf16_f32 v25, v20, v21
	global_store_dwordx4 v[30:31], v[22:25], off offset:1024 nt
	v_lshlrev_b32_e32 v31, 16, v23
	v_lshlrev_b32_e32 v30, 16, v22
	v_and_b32_e32 v23, 0xffff0000, v23
	v_and_b32_e32 v22, 0xffff0000, v22
	v_pk_mul_f32 v[22:23], v[22:23], v[22:23]
	s_nop 0
	v_pk_fma_f32 v[22:23], v[30:31], v[30:31], v[22:23]
	s_nop 0
	v_add_f32_e32 v22, v42, v22
	v_add_f32_e32 v30, v22, v23
	v_lshlrev_b32_e32 v23, 16, v25
	v_lshlrev_b32_e32 v22, 16, v24
	v_and_b32_e32 v25, 0xffff0000, v25
	v_and_b32_e32 v24, 0xffff0000, v24
	v_pk_mul_f32 v[24:25], v[24:25], v[24:25]
	s_nop 0
	v_pk_fma_f32 v[22:23], v[22:23], v[22:23], v[24:25]
	s_nop 0
	v_add_f32_e32 v22, v30, v22
	v_add_f32_e32 v22, v22, v23
	s_cbranch_execnz .LBB0_138
.LBB0_140:
	v_mov_b32_e32 v22, v42
	global_store_dwordx4 v[32:33], v[26:29], off offset:2048 nt
	global_store_dwordx4 v[32:33], v[18:21], off offset:2064 nt
	s_and_b64 vcc, exec, s[44:45]
	s_cbranch_vccnz .LBB0_102

.LBB0_301:
	s_or_b64 exec, exec, s[46:47]
	s_waitcnt vmcnt(4)
	ds_bpermute_b32 v70, v63, v69
	v_ashrrev_i32_e32 v19, 31, v18
	v_lshlrev_b64 v[18:19], 11, v[18:19]
	v_lshl_add_u64 v[20:21], v[52:53], 0, v[18:19]
	v_lshl_add_u64 v[22:23], v[54:55], 0, v[18:19]
	s_waitcnt lgkmcnt(0)
	v_add_f32_e32 v69, v69, v70
	ds_bpermute_b32 v70, v64, v69
	global_load_dwordx4 v[26:29], v[20:21], off
	global_load_dwordx4 v[30:33], v[22:23], off
	s_nop 0
	global_load_dwordx4 v[18:21], v[20:21], off offset:1024
	s_nop 0
	global_load_dwordx4 v[22:25], v[22:23], off offset:1024
	s_waitcnt lgkmcnt(0)
	v_add_f32_e32 v69, v69, v70
	ds_bpermute_b32 v70, v65, v69
	s_waitcnt lgkmcnt(0)
	v_add_f32_e32 v69, v69, v70
	ds_bpermute_b32 v70, v66, v69
	s_waitcnt lgkmcnt(0)
	v_add_f32_e32 v69, v69, v70
	ds_bpermute_b32 v70, v67, v69
	s_waitcnt lgkmcnt(0)
	v_add_f32_e32 v69, v69, v70
	ds_bpermute_b32 v70, v68, v69
	s_waitcnt lgkmcnt(0)
	v_add_f32_e32 v69, v69, v70
	v_fmamk_f32 v69, v69, 0x3a800000, v229
	v_cmp_gt_f32_e32 vcc, s5, v69
	v_mul_f32_e32 v70, 0x4f800000, v69
	s_nop 0
	v_cndmask_b32_e32 v69, v69, v70, vcc
	v_sqrt_f32_e32 v70, v69
	s_nop 0
	v_add_u32_e32 v71, -1, v70
	v_fma_f32 v72, -v71, v70, v69
	v_cmp_ge_f32_e64 s[46:47], 0, v72
	v_add_u32_e32 v72, 1, v70
	s_nop 0
	v_cndmask_b32_e64 v71, v70, v71, s[46:47]
	v_fma_f32 v70, -v72, v70, v69
	v_cmp_lt_f32_e64 s[46:47], 0, v70
	s_nop 1
	v_cndmask_b32_e64 v70, v71, v72, s[46:47]
	v_mul_f32_e32 v71, 0x37800000, v70
	v_cndmask_b32_e32 v70, v70, v71, vcc
	v_cmp_class_f32_e32 vcc, v69, v230
	s_nop 1
	v_cndmask_b32_e32 v69, v70, v69, vcc
	v_div_scale_f32 v70, s[16:17], v69, v69, 1.0
	v_rcp_f32_e32 v71, v70
	s_nop 0
	v_fma_f32 v72, -v70, v71, 1.0
	v_fmac_f32_e32 v71, v72, v71
	v_div_scale_f32 v72, vcc, 1.0, v69, 1.0
	v_mul_f32_e32 v73, v72, v71
	v_fma_f32 v74, -v70, v73, v72
	v_fmac_f32_e32 v73, v74, v71
	v_fma_f32 v70, -v70, v73, v72
	v_div_fmas_f32 v70, v70, v71, v73
	v_div_fixup_f32 v69, v70, v69, 1.0
	s_waitcnt vmcnt(5)
	v_lshlrev_b32_e32 v71, 16, v46
	v_lshlrev_b32_e32 v70, 16, v42
	v_mul_f32_e32 v71, v69, v71
	v_and_b32_e32 v46, 0xffff0000, v46
	v_fmac_f32_e32 v70, v6, v71
	v_and_b32_e32 v42, 0xffff0000, v42
	v_mul_f32_e32 v46, v69, v46
	v_lshlrev_b32_e32 v71, 16, v47
	v_fmac_f32_e32 v42, v7, v46
	v_lshlrev_b32_e32 v46, 16, v43
	v_mul_f32_e32 v71, v69, v71
	v_and_b32_e32 v47, 0xffff0000, v47
	v_fmac_f32_e32 v46, v8, v71
	v_and_b32_e32 v43, 0xffff0000, v43
	v_mul_f32_e32 v47, v69, v47
	v_lshlrev_b32_e32 v71, 16, v48
	v_fmac_f32_e32 v43, v9, v47
	v_lshlrev_b32_e32 v47, 16, v44
	v_mul_f32_e32 v71, v69, v71
	v_and_b32_e32 v48, 0xffff0000, v48
	v_fmac_f32_e32 v47, v14, v71
	v_and_b32_e32 v44, 0xffff0000, v44
	v_mul_f32_e32 v48, v69, v48
	v_lshlrev_b32_e32 v71, 16, v49
	v_and_b32_e32 v49, 0xffff0000, v49
	v_fmac_f32_e32 v44, v15, v48
	v_lshlrev_b32_e32 v48, 16, v45
	v_and_b32_e32 v45, 0xffff0000, v45
	v_mul_f32_e32 v49, v69, v49
	v_mul_f32_e32 v71, v69, v71
	v_fmac_f32_e32 v45, v17, v49
	v_cvt_pk_bf16_f32 v42, v70, v42
	v_fmac_f32_e32 v48, v16, v71
	v_cvt_pk_bf16_f32 v43, v46, v43
	v_cvt_pk_bf16_f32 v44, v47, v44
	v_cvt_pk_bf16_f32 v45, v48, v45
	global_store_dwordx4 v[60:61], v[42:45], off nt
	v_lshlrev_b32_e32 v46, 16, v42
	s_nop 0
	v_and_b32_e32 v42, 0xffff0000, v42
	v_mul_f32_e32 v42, v42, v42
	v_fmac_f32_e32 v42, v46, v46
	v_lshlrev_b32_e32 v46, 16, v43
	v_and_b32_e32 v43, 0xffff0000, v43
	v_mul_f32_e32 v43, v43, v43
	v_fmac_f32_e32 v43, v46, v46
	v_add_f32_e32 v42, v42, v43
	v_lshlrev_b32_e32 v43, 16, v44
	v_and_b32_e32 v44, 0xffff0000, v44
	v_mul_f32_e32 v44, v44, v44
	v_fmac_f32_e32 v44, v43, v43
	v_add_f32_e32 v42, v42, v44
	v_and_b32_e32 v44, 0xffff0000, v45
	v_lshlrev_b32_e32 v43, 16, v45
	v_mul_f32_e32 v44, v44, v44
	v_fmac_f32_e32 v44, v43, v43
	v_add_f32_e32 v42, v42, v44
	s_waitcnt vmcnt(5)
	v_lshlrev_b32_e32 v44, 16, v38
	v_lshlrev_b32_e32 v43, 16, v34
	v_mul_f32_e32 v44, v69, v44
	v_and_b32_e32 v38, 0xffff0000, v38
	v_fmac_f32_e32 v43, v10, v44
	v_and_b32_e32 v34, 0xffff0000, v34
	v_mul_f32_e32 v38, v69, v38
	v_lshlrev_b32_e32 v44, 16, v39
	v_fmac_f32_e32 v34, v11, v38
	v_lshlrev_b32_e32 v38, 16, v35
	v_mul_f32_e32 v44, v69, v44
	v_and_b32_e32 v39, 0xffff0000, v39
	v_fmac_f32_e32 v38, v12, v44
	v_and_b32_e32 v35, 0xffff0000, v35
	v_mul_f32_e32 v39, v69, v39
	v_lshlrev_b32_e32 v44, 16, v40
	v_fmac_f32_e32 v35, v13, v39
	v_lshlrev_b32_e32 v39, 16, v36
	v_mul_f32_e32 v44, v69, v44
	v_and_b32_e32 v40, 0xffff0000, v40
	v_fmac_f32_e32 v39, v2, v44
	v_and_b32_e32 v36, 0xffff0000, v36
	v_mul_f32_e32 v40, v69, v40
	v_lshlrev_b32_e32 v44, 16, v41
	v_and_b32_e32 v41, 0xffff0000, v41
	v_fmac_f32_e32 v36, v3, v40
	v_lshlrev_b32_e32 v40, 16, v37
	v_and_b32_e32 v37, 0xffff0000, v37
	v_mul_f32_e32 v41, v69, v41
	v_mul_f32_e32 v44, v69, v44
	v_fmac_f32_e32 v37, v5, v41
	v_cvt_pk_bf16_f32 v34, v43, v34
	v_fmac_f32_e32 v40, v4, v44
	v_cvt_pk_bf16_f32 v35, v38, v35
	v_cvt_pk_bf16_f32 v36, v39, v36
	v_cvt_pk_bf16_f32 v37, v40, v37
	global_store_dwordx4 v[60:61], v[34:37], off offset:1024 nt
	v_lshlrev_b32_e32 v38, 16, v34
	s_nop 0
	v_and_b32_e32 v34, 0xffff0000, v34
	v_mul_f32_e32 v34, v34, v34
	v_fmac_f32_e32 v34, v38, v38
	v_lshlrev_b32_e32 v38, 16, v35
	v_and_b32_e32 v35, 0xffff0000, v35
	v_mul_f32_e32 v35, v35, v35
	v_add_f32_e32 v34, v42, v34
	v_fmac_f32_e32 v35, v38, v38
	v_add_f32_e32 v34, v34, v35
	v_lshlrev_b32_e32 v35, 16, v36
	v_and_b32_e32 v36, 0xffff0000, v36
	v_mul_f32_e32 v36, v36, v36
	v_fmac_f32_e32 v36, v35, v35
	v_add_f32_e32 v34, v34, v36
	v_and_b32_e32 v36, 0xffff0000, v37
	v_lshlrev_b32_e32 v35, 16, v37
	v_mul_f32_e32 v36, v36, v36
	v_fmac_f32_e32 v36, v35, v35
	v_add_f32_e32 v34, v34, v36
	ds_bpermute_b32 v35, v63, v34
	s_waitcnt lgkmcnt(0)
	v_add_f32_e32 v34, v34, v35
	ds_bpermute_b32 v35, v64, v34
	s_waitcnt lgkmcnt(0)
	v_add_f32_e32 v34, v34, v35
	ds_bpermute_b32 v35, v65, v34
	s_waitcnt lgkmcnt(0)
	v_add_f32_e32 v34, v34, v35
	ds_bpermute_b32 v35, v66, v34
	s_waitcnt lgkmcnt(0)
	v_add_f32_e32 v34, v34, v35
	ds_bpermute_b32 v35, v67, v34
	s_waitcnt lgkmcnt(0)
	v_add_f32_e32 v34, v34, v35
	ds_bpermute_b32 v35, v68, v34
	s_and_saveexec_b64 s[68:69], s[42:43]
	s_cbranch_execz .LBB0_303
	s_waitcnt lgkmcnt(0)
	v_add_f32_e32 v34, v34, v35
	v_fmamk_f32 v34, v34, 0x3a800000, v229
	v_mul_f32_e32 v35, 0x4f800000, v34
	v_cmp_gt_f32_e32 vcc, s5, v34
	s_nop 1
	v_cndmask_b32_e32 v34, v34, v35, vcc
	v_sqrt_f32_e32 v35, v34
	s_nop 0
	v_add_u32_e32 v36, -1, v35
	v_fma_f32 v38, -v36, v35, v34
	v_add_u32_e32 v37, 1, v35
	v_cmp_ge_f32_e64 s[46:47], 0, v38
	s_nop 1
	v_cndmask_b32_e64 v36, v35, v36, s[46:47]
	v_fma_f32 v35, -v37, v35, v34
	v_cmp_lt_f32_e64 s[46:47], 0, v35
	s_nop 1
	v_cndmask_b32_e64 v35, v36, v37, s[46:47]
	v_mul_f32_e32 v36, 0x37800000, v35
	v_cndmask_b32_e32 v35, v35, v36, vcc
	v_cmp_class_f32_e32 vcc, v34, v230
	s_nop 1
	v_cndmask_b32_e32 v34, v35, v34, vcc
	v_div_scale_f32 v35, s[16:17], v34, v34, 1.0
	v_rcp_f32_e32 v36, v35
	s_nop 0
	v_fma_f32 v37, -v35, v36, 1.0
	v_fmac_f32_e32 v36, v37, v36
	v_div_scale_f32 v37, vcc, 1.0, v34, 1.0
	v_mul_f32_e32 v38, v37, v36
	v_fma_f32 v39, -v35, v38, v37
	v_fmac_f32_e32 v38, v39, v36
	v_fma_f32 v35, -v35, v38, v37
	v_div_fmas_f32 v35, v35, v36, v38
	v_div_fixup_f32 v36, v35, v34, 1.0
	v_lshl_add_u64 v[34:35], v[58:59], 2, s[86:87]
	global_store_dword v[34:35], v36, off
.LBB0_303:
	s_or_b64 exec, exec, s[68:69]
	s_and_saveexec_b64 s[46:47], s[44:45]
	s_cbranch_execz .LBB0_284
	ds_bpermute_b32 v34, v63, v57
	s_waitcnt vmcnt(4)
	v_lshlrev_b32_e32 v37, 16, v30
	v_and_b32_e32 v30, 0xffff0000, v30
	v_lshlrev_b32_e32 v39, 16, v31
	v_and_b32_e32 v31, 0xffff0000, v31
	s_waitcnt lgkmcnt(0)
	v_add_f32_e32 v34, v57, v34
	ds_bpermute_b32 v35, v64, v34
	v_lshlrev_b32_e32 v36, 16, v26
	v_and_b32_e32 v26, 0xffff0000, v26
	v_lshlrev_b32_e32 v38, 16, v27
	v_and_b32_e32 v27, 0xffff0000, v27
	s_waitcnt lgkmcnt(0)
	v_add_f32_e32 v34, v34, v35
	ds_bpermute_b32 v35, v65, v34
	v_lshlrev_b32_e32 v41, 16, v32
	v_and_b32_e32 v32, 0xffff0000, v32
	v_lshlrev_b32_e32 v40, 16, v28
	v_and_b32_e32 v28, 0xffff0000, v28
	s_waitcnt lgkmcnt(0)
	v_add_f32_e32 v34, v34, v35
	ds_bpermute_b32 v35, v66, v34
	v_ashrrev_i32_e32 v57, 31, v56
	s_waitcnt lgkmcnt(0)
	v_add_f32_e32 v34, v34, v35
	ds_bpermute_b32 v35, v67, v34
	s_waitcnt lgkmcnt(0)
	v_add_f32_e32 v34, v34, v35
	ds_bpermute_b32 v35, v68, v34
	s_waitcnt lgkmcnt(0)
	v_add_f32_e32 v34, v34, v35
	v_fmamk_f32 v34, v34, 0x3a800000, v229
	v_mul_f32_e32 v35, 0x4f800000, v34
	v_cmp_gt_f32_e32 vcc, s5, v34
	s_nop 1
	v_cndmask_b32_e32 v34, v34, v35, vcc
	v_sqrt_f32_e32 v35, v34
	s_nop 0
	v_add_u32_e32 v42, -1, v35
	v_add_u32_e32 v43, 1, v35
	v_fma_f32 v44, -v42, v35, v34
	v_fma_f32 v45, -v43, v35, v34
	v_cmp_ge_f32_e64 s[44:45], 0, v44
	s_nop 1
	v_cndmask_b32_e64 v35, v35, v42, s[44:45]
	v_cmp_lt_f32_e64 s[44:45], 0, v45
	s_nop 1
	v_cndmask_b32_e64 v35, v35, v43, s[44:45]
	v_mul_f32_e32 v42, 0x37800000, v35
	v_cndmask_b32_e32 v35, v35, v42, vcc
	v_cmp_class_f32_e32 vcc, v34, v230
	s_nop 1
	v_cndmask_b32_e32 v34, v35, v34, vcc
	v_div_scale_f32 v35, s[16:17], v34, v34, 1.0
	v_rcp_f32_e32 v42, v35
	v_div_scale_f32 v43, vcc, 1.0, v34, 1.0
	v_fma_f32 v44, -v35, v42, 1.0
	v_fmac_f32_e32 v42, v44, v42
	v_mul_f32_e32 v44, v43, v42
	v_fma_f32 v45, -v35, v44, v43
	v_fmac_f32_e32 v44, v45, v42
	v_fma_f32 v35, -v35, v44, v43
	v_div_fmas_f32 v35, v35, v42, v44
	v_div_fixup_f32 v34, v35, v34, 1.0
	v_mul_f32_e32 v30, v34, v30
	v_mul_f32_e32 v31, v34, v31
	v_fmac_f32_e32 v26, v7, v30
	v_fmac_f32_e32 v27, v9, v31
	v_mul_f32_e32 v30, v34, v32
	v_lshlrev_b32_e32 v31, 16, v33
	v_fmac_f32_e32 v28, v15, v30
	v_lshlrev_b32_e32 v30, 16, v29
	v_mul_f32_e32 v31, v34, v31
	v_fmac_f32_e32 v30, v16, v31
	v_and_b32_e32 v31, 0xffff0000, v33
	v_mul_f32_e32 v35, v34, v37
	v_and_b32_e32 v29, 0xffff0000, v29
	v_mul_f32_e32 v31, v34, v31
	v_mul_f32_e32 v37, v34, v39
	v_fmac_f32_e32 v36, v6, v35
	v_fmac_f32_e32 v29, v17, v31
	v_cvt_pk_bf16_f32 v26, v36, v26
	v_fmac_f32_e32 v38, v8, v37
	v_and_b32_e32 v31, 0xffff0000, v26
	v_cvt_pk_bf16_f32 v27, v38, v27
	v_cvt_pk_bf16_f32 v29, v30, v29
	v_lshlrev_b32_e32 v30, 16, v26
	v_mul_f32_e32 v31, v31, v31
	v_and_b32_e32 v32, 0xffff0000, v27
	v_fmac_f32_e32 v31, v30, v30
	v_lshlrev_b32_e32 v30, 16, v27
	v_mul_f32_e32 v32, v32, v32
	v_mul_f32_e32 v39, v34, v41
	v_fmac_f32_e32 v32, v30, v30
	v_fmac_f32_e32 v40, v14, v39
	v_cvt_pk_bf16_f32 v28, v40, v28
	v_add_f32_e32 v30, v31, v32
	v_and_b32_e32 v32, 0xffff0000, v28
	v_lshlrev_b32_e32 v31, 16, v28
	v_mul_f32_e32 v32, v32, v32
	v_fmac_f32_e32 v32, v31, v31
	v_add_f32_e32 v30, v30, v32
	v_and_b32_e32 v32, 0xffff0000, v29
	v_lshlrev_b32_e32 v31, 16, v29
	v_mul_f32_e32 v32, v32, v32
	v_fmac_f32_e32 v32, v31, v31
	v_add_f32_e32 v30, v30, v32
	s_waitcnt vmcnt(2)
	v_lshlrev_b32_e32 v32, 16, v22
	v_lshlrev_b32_e32 v31, 16, v18
	v_mul_f32_e32 v32, v34, v32
	v_and_b32_e32 v22, 0xffff0000, v22
	v_fmac_f32_e32 v31, v10, v32
	v_and_b32_e32 v18, 0xffff0000, v18
	v_mul_f32_e32 v22, v34, v22
	v_lshlrev_b32_e32 v32, 16, v23
	v_fmac_f32_e32 v18, v11, v22
	v_lshlrev_b32_e32 v22, 16, v19
	v_mul_f32_e32 v32, v34, v32
	v_and_b32_e32 v23, 0xffff0000, v23
	v_fmac_f32_e32 v22, v12, v32
	v_and_b32_e32 v19, 0xffff0000, v19
	v_mul_f32_e32 v23, v34, v23
	v_lshlrev_b32_e32 v32, 16, v24
	v_fmac_f32_e32 v19, v13, v23
	v_lshlrev_b32_e32 v23, 16, v20
	v_mul_f32_e32 v32, v34, v32
	v_fmac_f32_e32 v23, v2, v32
	v_and_b32_e32 v32, 0xffff0000, v20
	v_and_b32_e32 v20, 0xffff0000, v24
	v_mul_f32_e32 v20, v34, v20
	v_fmac_f32_e32 v32, v3, v20
	v_lshlrev_b32_e32 v20, 16, v25
	v_lshlrev_b32_e32 v24, 16, v21
	v_mul_f32_e32 v20, v34, v20
	v_fmac_f32_e32 v24, v4, v20
	v_and_b32_e32 v20, 0xffff0000, v25
	v_and_b32_e32 v33, 0xffff0000, v21
	v_mul_f32_e32 v20, v34, v20
	v_fmac_f32_e32 v33, v5, v20
	v_cvt_pk_bf16_f32 v20, v31, v18
	v_cvt_pk_bf16_f32 v21, v22, v19
	v_cvt_pk_bf16_f32 v22, v23, v32
	v_cvt_pk_bf16_f32 v23, v24, v33
	s_nop 0
	v_and_b32_e32 v19, 0xffff0000, v20
	v_lshlrev_b32_e32 v18, 16, v20
	v_mul_f32_e32 v19, v19, v19
	v_fmac_f32_e32 v19, v18, v18
	v_and_b32_e32 v24, 0xffff0000, v21
	v_add_f32_e32 v18, v30, v19
	v_lshlrev_b32_e32 v19, 16, v21
	v_mul_f32_e32 v24, v24, v24
	v_fmac_f32_e32 v24, v19, v19
	v_add_f32_e32 v18, v18, v24
	v_and_b32_e32 v24, 0xffff0000, v22
	v_lshlrev_b32_e32 v19, 16, v22
	v_mul_f32_e32 v24, v24, v24
	v_fmac_f32_e32 v24, v19, v19
	v_add_f32_e32 v18, v18, v24
	v_and_b32_e32 v24, 0xffff0000, v23
	v_lshlrev_b32_e32 v19, 16, v23
	v_mul_f32_e32 v24, v24, v24
	v_fmac_f32_e32 v24, v19, v19
	v_add_f32_e32 v18, v18, v24
	ds_bpermute_b32 v19, v63, v18
	v_lshlrev_b64 v[24:25], 11, v[56:57]
	v_lshl_add_u64 v[24:25], v[52:53], 0, v[24:25]
	global_store_dwordx4 v[24:25], v[26:29], off nt
	global_store_dwordx4 v[24:25], v[20:23], off offset:1024 nt
	s_waitcnt lgkmcnt(0)
	v_add_f32_e32 v18, v18, v19
	ds_bpermute_b32 v19, v64, v18
	s_waitcnt lgkmcnt(0)
	v_add_f32_e32 v18, v18, v19
	ds_bpermute_b32 v19, v65, v18
	s_waitcnt lgkmcnt(0)
	v_add_f32_e32 v18, v18, v19
	ds_bpermute_b32 v19, v66, v18
	s_waitcnt lgkmcnt(0)
	v_add_f32_e32 v18, v18, v19
	ds_bpermute_b32 v19, v67, v18
	s_waitcnt lgkmcnt(0)
	v_add_f32_e32 v18, v18, v19
	ds_bpermute_b32 v19, v68, v18
	s_and_b64 exec, exec, s[42:43]
	s_cbranch_execz .LBB0_284
	s_waitcnt lgkmcnt(0)
	v_add_f32_e32 v18, v18, v19
	v_fmamk_f32 v18, v18, 0x3a800000, v229
	v_mul_f32_e32 v19, 0x4f800000, v18
	v_cmp_gt_f32_e32 vcc, s5, v18
	s_nop 1
	v_cndmask_b32_e32 v18, v18, v19, vcc
	v_sqrt_f32_e32 v19, v18
	s_nop 0
	v_add_u32_e32 v20, -1, v19
	v_fma_f32 v22, -v20, v19, v18
	v_add_u32_e32 v21, 1, v19
	v_cmp_ge_f32_e64 s[44:45], 0, v22
	s_nop 1
	v_cndmask_b32_e64 v20, v19, v20, s[44:45]
	v_fma_f32 v19, -v21, v19, v18
	v_cmp_lt_f32_e64 s[44:45], 0, v19
	s_nop 1
	v_cndmask_b32_e64 v19, v20, v21, s[44:45]
	v_mul_f32_e32 v20, 0x37800000, v19
	v_cndmask_b32_e32 v19, v19, v20, vcc
	v_cmp_class_f32_e32 vcc, v18, v230
	s_nop 1
	v_cndmask_b32_e32 v18, v19, v18, vcc
	v_div_scale_f32 v19, s[16:17], v18, v18, 1.0
	v_rcp_f32_e32 v20, v19
	s_nop 0
	v_fma_f32 v21, -v19, v20, 1.0
	v_fmac_f32_e32 v20, v21, v20
	v_div_scale_f32 v21, vcc, 1.0, v18, 1.0
	v_mul_f32_e32 v22, v21, v20
	v_fma_f32 v23, -v19, v22, v21
	v_fmac_f32_e32 v22, v23, v20
	v_fma_f32 v19, -v19, v22, v21
	v_div_fmas_f32 v19, v19, v20, v22
	v_div_fixup_f32 v20, v19, v18, 1.0
	v_lshl_add_u64 v[18:19], v[56:57], 2, s[86:87]
	global_store_dword v[18:19], v20, off
	s_branch .LBB0_284
